# peeled first K iteration: skip the two vmcnt(8) waits after an rst-table epilogue (data already drained) so epilogue store acks overlap the first two super-phases
# baseline (speedup 1.0000x reference)
; #define PG8_STAGE(bufoff, gbase, voff) do { _Pragma("unroll") for (int _i = 0; _i < 2; ++_i) \
;         __builtin_amdgcn_global_load_lds((const unsigned*)((const char*)(gbase) + (size_t)_i * r64 + (voff)), (PG8_LAS unsigned*)(lds + (bufoff) + ldsw + _i * 8192), 16, 0, 0); } while (0)
; #define PG8_LDA(dst, b, h) do { _Pragma("unroll") for (int m = 0; m < 4; ++m) _Pragma("unroll") for (int k = 0; k < 2; ++k) dst[m][k] = *(const PG8_LAS bf16x8*)(lds + PG8_SA(b, h) + aoff + m * 2048 + k * 1024); } while (0)
; #define PG8_LDB(dst, b, h) do { _Pragma("unroll") for (int n = 0; n < 2; ++n) _Pragma("unroll") for (int k = 0; k < 2; ++k) dst[n][k] = *(const PG8_LAS bf16x8*)(lds + PG8_SB(b, h) + boff + n * 2048 + k * 1024); } while (0)
; #define PG8_MMA(ai, bj, At, Bt) do { __builtin_amdgcn_s_setprio(1); _Pragma("unroll") for (int m = 0; m < 4; ++m) _Pragma("unroll") for (int n = 0; n < 2; ++n) _Pragma("unroll") for (int k = 0; k < 2; ++k) \
;         acc[ai][bj][m][n] = __builtin_amdgcn_mfma_f32_16x16x32_bf16(Bt[n][k], At[m][k], acc[ai][bj][m][n], 0, 0, 0); __builtin_amdgcn_s_setprio(0); } while (0)
; #define PG8_WAIT_V(n) asm volatile("s_waitcnt vmcnt(" #n ")" ::: "memory")
; #define PG8_WAIT_L(n) asm volatile("s_waitcnt lgkmcnt(" #n ")" ::: "memory")
; #define PG8_BAR __builtin_amdgcn_s_barrier()
; template <class Epi, class Sched, bool ALIGN_EPI = false, bool SP2 = false>
; __device__ __forceinline__ void gemm_phase(PG8_LAS unsigned char* lds, const Gemm g, const Sched& S, const Epi& E) {
;     ...
;         for (int t = 0; t < nt; t += 2) {
;             const bool last = (t == nt - 2);
;             const char* a1 = cA + (size_t)(t + 1) * kstep;
;             const char* a2 = last ? nA : cA + (size_t)(t + 2) * kstep; const char* b2 = last ? nB : cB + (size_t)(t + 2) * kstep;
;             const char* a3 = a2 + kstep; const char* b3 = b2 + kstep;
;             if (last && has_next) S.a_ready(nxt);
;             if constexpr (SP2) {
;             PG8_LDB(B0, 0, 0); PG8_LDB(B1, 0, 1); PG8_SCHED; PG8_LDA(At, 0, 0); PG8_STAGE(PG8_SA(1, 1), a1 + hstep, voffA);
;             PG8_WAIT_V(8); PG8_WAIT_L(0); PG8_BAR; PG8_MMA(0, 0, At, B0); PG8_MMA(0, 1, At, B1); PG8_BAR; PG8_SCHED;
;             PG8_LDA(At, 0, 1); PG8_STAGE(PG8_SB(0, 0), b2, voffB); PG8_STAGE(PG8_SB(0, 1), b2 + hstep, voffB); PG8_STAGE(PG8_SA(0, 0), a2, voffA);
.LBB0_167:
	s_sub_i32 s32, s33, 1
	s_min_u32 s32, s32, 1
	s_andn2_b32 s32, s32, s15
	v_and_b32_e32 v2, 63, v214
	s_lshl_b32 s12, s45, 14
	s_lshl_b32 s3, s41, 1
	v_lshlrev_b32_e32 v2, 4, v2
	s_add_u32 s12, s12, s3
	s_add_u32 s12, s64, s12
	s_addc_u32 s13, s65, 0
	s_add_i32 m0, s3, 0x21000
	s_nop 0
	global_load_lds_dwordx4 v2, s[12:13]
	global_load_lds_dwordx4 v2, s[12:13] offset:1024
	s_add_u32 s6, s10, 0x80
	s_addc_u32 s7, s11, 0
	s_add_u32 s10, s8, 0x100
	s_addc_u32 s11, s9, 0
	s_mov_b32 s8, 0
	s_add_i32 s12, s8, 2
	s_add_u32 s3, s6, 0x80
	s_addc_u32 s9, s7, 0
	s_add_i32 s13, 0, 0x10000
	s_cmp_eq_u32 s70, s8
	s_cselect_b32 s9, s93, s9
	s_cselect_b32 s8, s92, s3
	s_cselect_b32 s19, s95, s11
	s_cselect_b32 s18, s94, s10
	s_add_i32 s3, 0, 0x14000
	v_add_u32_e32 v14, s13, v242
	v_add_u32_e32 v30, s3, v242
	s_waitcnt lgkmcnt(0)
	ds_read_b128 v[2:5], v14
	ds_read_b128 v[6:9], v14 offset:1024
	ds_read_b128 v[10:13], v14 offset:2048
	ds_read_b128 v[14:17], v14 offset:3072
	ds_read_b128 v[18:21], v30
	ds_read_b128 v[22:25], v30 offset:1024
	ds_read_b128 v[26:29], v30 offset:2048
	ds_read_b128 v[30:33], v30 offset:3072
	v_lshl_add_u64 v[194:195], s[6:7], 0, v[218:219]
	s_add_i32 m0, s90, 0xc000
	ds_read_b128 v[34:37], v243
	ds_read_b128 v[38:41], v243 offset:1024
	ds_read_b128 v[42:45], v243 offset:2048
	ds_read_b128 v[46:49], v243 offset:3072
	ds_read_b128 v[50:53], v243 offset:4096
	ds_read_b128 v[54:57], v243 offset:5120
	ds_read_b128 v[58:61], v243 offset:6144
	ds_read_b128 v[62:65], v243 offset:7168
	global_load_lds_dwordx4 v[194:195], off
	v_lshl_add_u64 v[194:195], s[6:7], 0, v[220:221]
	s_add_i32 m0, s90, 0xe000
	s_nop 0
	global_load_lds_dwordx4 v[194:195], off
	s_cmp_lg_u32 s32, 0
	s_cbranch_scc1 .Lpeel_nowait0
	s_waitcnt vmcnt(8)
.Lpeel_nowait0:
	s_waitcnt lgkmcnt(0)
	s_barrier
	s_setprio 1
	s_waitcnt lgkmcnt(0)
	v_mfma_f32_16x16x32_bf16 v[190:193], v[2:5], v[34:37], 0
	v_mfma_f32_16x16x32_bf16 v[186:189], v[10:13], v[34:37], 0
	v_mfma_f32_16x16x32_bf16 v[174:177], v[2:5], v[42:45], 0
	v_mfma_f32_16x16x32_bf16 v[170:173], v[10:13], v[42:45], 0
	v_mfma_f32_16x16x32_bf16 v[158:161], v[2:5], v[50:53], 0
	v_mfma_f32_16x16x32_bf16 v[154:157], v[10:13], v[50:53], 0
	v_mfma_f32_16x16x32_bf16 v[142:145], v[2:5], v[58:61], 0
	v_mfma_f32_16x16x32_bf16 v[138:141], v[10:13], v[58:61], 0
	v_mfma_f32_16x16x32_bf16 v[190:193], v[6:9], v[38:41], v[190:193]
	v_mfma_f32_16x16x32_bf16 v[186:189], v[14:17], v[38:41], v[186:189]
	v_mfma_f32_16x16x32_bf16 v[174:177], v[6:9], v[46:49], v[174:177]
	v_mfma_f32_16x16x32_bf16 v[170:173], v[14:17], v[46:49], v[170:173]
	v_mfma_f32_16x16x32_bf16 v[158:161], v[6:9], v[54:57], v[158:161]
	v_mfma_f32_16x16x32_bf16 v[154:157], v[14:17], v[54:57], v[154:157]
	v_mfma_f32_16x16x32_bf16 v[142:145], v[6:9], v[62:65], v[142:145]
	v_mfma_f32_16x16x32_bf16 v[138:141], v[14:17], v[62:65], v[138:141]
	s_setprio 0
	s_setprio 1
	v_mfma_f32_16x16x32_bf16 v[182:185], v[18:21], v[34:37], 0
	v_mfma_f32_16x16x32_bf16 v[34:37], v[26:29], v[34:37], 0
	v_mfma_f32_16x16x32_bf16 v[182:185], v[22:25], v[38:41], v[182:185]
	v_mfma_f32_16x16x32_bf16 v[34:37], v[30:33], v[38:41], v[34:37]
	v_mfma_f32_16x16x32_bf16 v[38:41], v[18:21], v[42:45], 0
	v_mfma_f32_16x16x32_bf16 v[42:45], v[26:29], v[42:45], 0
	v_mfma_f32_16x16x32_bf16 v[38:41], v[22:25], v[46:49], v[38:41]
	v_mfma_f32_16x16x32_bf16 v[42:45], v[30:33], v[46:49], v[42:45]
	v_mfma_f32_16x16x32_bf16 v[46:49], v[18:21], v[50:53], 0
	v_mfma_f32_16x16x32_bf16 v[50:53], v[26:29], v[50:53], 0
	v_mfma_f32_16x16x32_bf16 v[46:49], v[22:25], v[54:57], v[46:49]
	v_mfma_f32_16x16x32_bf16 v[50:53], v[30:33], v[54:57], v[50:53]
	v_mfma_f32_16x16x32_bf16 v[54:57], v[18:21], v[58:61], 0
	v_mfma_f32_16x16x32_bf16 v[58:61], v[26:29], v[58:61], 0
	v_mfma_f32_16x16x32_bf16 v[54:57], v[22:25], v[62:65], v[54:57]
	v_mfma_f32_16x16x32_bf16 v[58:61], v[30:33], v[62:65], v[58:61]
	s_setprio 0
	s_barrier
	s_add_i32 s13, s13, s41
	v_lshl_add_u64 v[228:229], s[18:19], 0, v[0:1]
	s_mov_b32 m0, s13
	ds_read_b128 v[62:65], v243 offset:16384
	ds_read_b128 v[130:133], v243 offset:17408
	ds_read_b128 v[134:137], v243 offset:18432
	ds_read_b128 v[146:149], v243 offset:19456
	ds_read_b128 v[150:153], v243 offset:20480
	ds_read_b128 v[162:165], v243 offset:21504
	ds_read_b128 v[166:169], v243 offset:22528
	ds_read_b128 v[178:181], v243 offset:23552
	global_load_lds_dwordx4 v[228:229], off
	s_add_i32 m0, s13, 0x2000
	s_add_u32 s18, s18, s58
	v_lshl_add_u64 v[230:231], v[228:229], 0, s[56:57]
	s_addc_u32 s19, s19, s59
	s_add_i32 s3, s3, s41
	global_load_lds_dwordx4 v[230:231], off
	v_lshl_add_u64 v[244:245], s[18:19], 0, v[0:1]
	s_mov_b32 m0, s3
	v_lshl_add_u64 v[246:247], v[244:245], 0, s[56:57]
	global_load_lds_dwordx4 v[244:245], off
	s_add_i32 m0, s3, 0x2000
	v_lshl_add_u64 v[248:249], s[8:9], 0, v[216:217]
	global_load_lds_dwordx4 v[246:247], off
	s_mov_b32 m0, s90
	v_lshl_add_u64 v[250:251], v[248:249], 0, s[56:57]
	global_load_lds_dwordx4 v[248:249], off
	s_mov_b32 m0, s91
	s_nop 0
	global_load_lds_dwordx4 v[250:251], off
	s_cmp_lg_u32 s32, 0
	s_cbranch_scc1 .Lpeel_nowait1
	s_waitcnt vmcnt(8)
; #define PG8_STAGE(bufoff, gbase, voff) do { _Pragma("unroll") for (int _i = 0; _i < 2; ++_i) \
;         __builtin_amdgcn_global_load_lds((const unsigned*)((const char*)(gbase) + (size_t)_i * r64 + (voff)), (PG8_LAS unsigned*)(lds + (bufoff) + ldsw + _i * 8192), 16, 0, 0); } while (0)
; #define PG8_LDA(dst, b, h) do { _Pragma("unroll") for (int m = 0; m < 4; ++m) _Pragma("unroll") for (int k = 0; k < 2; ++k) dst[m][k] = *(const PG8_LAS bf16x8*)(lds + PG8_SA(b, h) + aoff + m * 2048 + k * 1024); } while (0)
; #define PG8_LDB(dst, b, h) do { _Pragma("unroll") for (int n = 0; n < 2; ++n) _Pragma("unroll") for (int k = 0; k < 2; ++k) dst[n][k] = *(const PG8_LAS bf16x8*)(lds + PG8_SB(b, h) + boff + n * 2048 + k * 1024); } while (0)
; #define PG8_MMA(ai, bj, At, Bt) do { __builtin_amdgcn_s_setprio(1); _Pragma("unroll") for (int m = 0; m < 4; ++m) _Pragma("unroll") for (int n = 0; n < 2; ++n) _Pragma("unroll") for (int k = 0; k < 2; ++k) \
;         acc[ai][bj][m][n] = __builtin_amdgcn_mfma_f32_16x16x32_bf16(Bt[n][k], At[m][k], acc[ai][bj][m][n], 0, 0, 0); __builtin_amdgcn_s_setprio(0); } while (0)
; #define PG8_WAIT_V(n) asm volatile("s_waitcnt vmcnt(" #n ")" ::: "memory")
; #define PG8_WAIT_L(n) asm volatile("s_waitcnt lgkmcnt(" #n ")" ::: "memory")
; #define PG8_BAR __builtin_amdgcn_s_barrier()
; #define PG8_SCHED __builtin_amdgcn_sched_barrier(0)
; template <class Epi, class Sched, bool ALIGN_EPI = false, bool SP2 = false>
; __device__ __forceinline__ void gemm_phase(PG8_LAS unsigned char* lds, const Gemm g, const Sched& S, const Epi& E) {
;     ...
;             PG8_WAIT_V(8); PG8_WAIT_L(0); PG8_BAR; PG8_MMA(1, 0, At, B0); PG8_MMA(1, 1, At, B1); PG8_BAR; PG8_SCHED;
;             PG8_LDB(B0, 1, 0); PG8_LDB(B1, 1, 1); PG8_SCHED; PG8_LDA(At, 1, 0); PG8_STAGE(PG8_SA(0, 1), a2 + hstep, voffA);
;             PG8_WAIT_V(8); PG8_WAIT_L(0); PG8_BAR; PG8_MMA(0, 0, At, B0); PG8_MMA(0, 1, At, B1); PG8_BAR; PG8_SCHED;
.Lpeel_nowait1:
	s_waitcnt lgkmcnt(0)
	s_barrier
	s_setprio 1
	s_waitcnt lgkmcnt(0)
	v_mfma_f32_16x16x32_bf16 v[126:129], v[2:5], v[62:65], 0
	v_mfma_f32_16x16x32_bf16 v[122:125], v[10:13], v[62:65], 0
	v_mfma_f32_16x16x32_bf16 v[110:113], v[2:5], v[134:137], 0
	v_mfma_f32_16x16x32_bf16 v[106:109], v[10:13], v[134:137], 0
	v_mfma_f32_16x16x32_bf16 v[94:97], v[2:5], v[150:153], 0
	v_mfma_f32_16x16x32_bf16 v[90:93], v[10:13], v[150:153], 0
	v_mfma_f32_16x16x32_bf16 v[2:5], v[2:5], v[166:169], 0
	v_mfma_f32_16x16x32_bf16 v[126:129], v[6:9], v[130:133], v[126:129]
	v_mfma_f32_16x16x32_bf16 v[122:125], v[14:17], v[130:133], v[122:125]
	v_mfma_f32_16x16x32_bf16 v[110:113], v[6:9], v[146:149], v[110:113]
	v_mfma_f32_16x16x32_bf16 v[106:109], v[14:17], v[146:149], v[106:109]
	v_mfma_f32_16x16x32_bf16 v[94:97], v[6:9], v[162:165], v[94:97]
	v_mfma_f32_16x16x32_bf16 v[90:93], v[14:17], v[162:165], v[90:93]
	v_mfma_f32_16x16x32_bf16 v[2:5], v[6:9], v[178:181], v[2:5]
	v_mfma_f32_16x16x32_bf16 v[6:9], v[10:13], v[166:169], 0
	v_mfma_f32_16x16x32_bf16 v[6:9], v[14:17], v[178:181], v[6:9]
	s_setprio 0
	s_setprio 1
	v_mfma_f32_16x16x32_bf16 v[74:77], v[26:29], v[134:137], 0
	v_mfma_f32_16x16x32_bf16 v[98:101], v[30:33], v[146:149], v[74:77]
	v_mfma_f32_16x16x32_bf16 v[74:77], v[18:21], v[150:153], 0
	v_mfma_f32_16x16x32_bf16 v[10:13], v[18:21], v[62:65], 0
	v_mfma_f32_16x16x32_bf16 v[14:17], v[26:29], v[62:65], 0
	v_mfma_f32_16x16x32_bf16 v[62:65], v[18:21], v[134:137], 0
	v_mfma_f32_16x16x32_bf16 v[86:89], v[22:25], v[162:165], v[74:77]
	v_mfma_f32_16x16x32_bf16 v[74:77], v[26:29], v[150:153], 0
	v_mfma_f32_16x16x32_bf16 v[18:21], v[18:21], v[166:169], 0
	v_mfma_f32_16x16x32_bf16 v[10:13], v[22:25], v[130:133], v[10:13]
	v_mfma_f32_16x16x32_bf16 v[62:65], v[22:25], v[146:149], v[62:65]
	v_mfma_f32_16x16x32_bf16 v[82:85], v[30:33], v[162:165], v[74:77]
	v_mfma_f32_16x16x32_bf16 v[18:21], v[22:25], v[178:181], v[18:21]
	v_mfma_f32_16x16x32_bf16 v[22:25], v[26:29], v[166:169], 0
	v_mfma_f32_16x16x32_bf16 v[14:17], v[30:33], v[130:133], v[14:17]
	v_mfma_f32_16x16x32_bf16 v[22:25], v[30:33], v[178:181], v[22:25]
	s_setprio 0
	s_barrier
	s_add_i32 s3, 0, 0x18000
	s_add_i32 s13, 0, 0x1c000
	v_add_u32_e32 v70, s3, v242
	v_add_u32_e32 v74, s13, v242
	ds_read_b128 v[26:29], v70
	ds_read_b128 v[30:33], v70 offset:1024
	ds_read_b128 v[66:69], v70 offset:2048
	ds_read_b128 v[70:73], v70 offset:3072
	ds_read_b128 v[194:197], v74
	ds_read_b128 v[198:201], v74 offset:1024
	ds_read_b128 v[202:205], v74 offset:2048
	ds_read_b128 v[206:209], v74 offset:3072
	s_add_u32 s8, s8, s58
	s_addc_u32 s9, s9, s59
	s_mov_b32 m0, s36
	v_lshl_add_u64 v[134:135], s[8:9], 0, v[216:217]
	ds_read_b128 v[74:77], v243 offset:32768
	ds_read_b128 v[78:81], v243 offset:33792
	ds_read_b128 v[102:105], v243 offset:34816
	ds_read_b128 v[114:117], v243 offset:35840
	ds_read_b128 v[118:121], v243 offset:36864
	ds_read_b128 v[130:133], v243 offset:37888
	ds_read_b128 v[210:213], v243 offset:38912
	ds_read_b128 v[224:227], v243 offset:39936
	global_load_lds_dwordx4 v[134:135], off
	v_lshl_add_u64 v[134:135], v[134:135], 0, s[56:57]
	s_mov_b32 m0, s62
	s_nop 0
	global_load_lds_dwordx4 v[134:135], off
	s_waitcnt vmcnt(8)
	s_waitcnt lgkmcnt(0)
	s_barrier
	s_setprio 1
	s_waitcnt lgkmcnt(0)
	v_mfma_f32_16x16x32_bf16 v[134:137], v[26:29], v[74:77], v[190:193]
	v_mfma_f32_16x16x32_bf16 v[190:193], v[30:33], v[78:81], v[134:137]
	v_mfma_f32_16x16x32_bf16 v[134:137], v[66:69], v[74:77], v[186:189]
	v_mfma_f32_16x16x32_bf16 v[186:189], v[70:73], v[78:81], v[134:137]
	v_mfma_f32_16x16x32_bf16 v[134:137], v[26:29], v[102:105], v[174:177]
	v_mfma_f32_16x16x32_bf16 v[174:177], v[30:33], v[114:117], v[134:137]
	v_mfma_f32_16x16x32_bf16 v[134:137], v[66:69], v[102:105], v[170:173]
	v_mfma_f32_16x16x32_bf16 v[170:173], v[70:73], v[114:117], v[134:137]
	v_mfma_f32_16x16x32_bf16 v[134:137], v[26:29], v[118:121], v[158:161]
	v_mfma_f32_16x16x32_bf16 v[158:161], v[30:33], v[130:133], v[134:137]
	v_mfma_f32_16x16x32_bf16 v[134:137], v[66:69], v[118:121], v[154:157]
	v_mfma_f32_16x16x32_bf16 v[154:157], v[70:73], v[130:133], v[134:137]
	v_mfma_f32_16x16x32_bf16 v[134:137], v[26:29], v[210:213], v[142:145]
	v_mfma_f32_16x16x32_bf16 v[142:145], v[30:33], v[224:227], v[134:137]
	v_mfma_f32_16x16x32_bf16 v[134:137], v[66:69], v[210:213], v[138:141]
	v_mfma_f32_16x16x32_bf16 v[138:141], v[70:73], v[224:227], v[134:137]
	s_setprio 0
	s_setprio 1
	v_mfma_f32_16x16x32_bf16 v[34:37], v[202:205], v[74:77], v[34:37]
	v_mfma_f32_16x16x32_bf16 v[178:181], v[206:209], v[78:81], v[34:37]
	v_mfma_f32_16x16x32_bf16 v[34:37], v[194:197], v[102:105], v[38:41]
	v_mfma_f32_16x16x32_bf16 v[166:169], v[198:201], v[114:117], v[34:37]
	v_mfma_f32_16x16x32_bf16 v[34:37], v[202:205], v[102:105], v[42:45]
	v_mfma_f32_16x16x32_bf16 v[162:165], v[206:209], v[114:117], v[34:37]
	v_mfma_f32_16x16x32_bf16 v[34:37], v[194:197], v[118:121], v[46:49]
	v_mfma_f32_16x16x32_bf16 v[150:153], v[198:201], v[130:133], v[34:37]
	v_mfma_f32_16x16x32_bf16 v[34:37], v[202:205], v[118:121], v[50:53]
	v_mfma_f32_16x16x32_bf16 v[134:137], v[194:197], v[74:77], v[182:185]
	v_mfma_f32_16x16x32_bf16 v[146:149], v[206:209], v[130:133], v[34:37]
	v_mfma_f32_16x16x32_bf16 v[34:37], v[194:197], v[210:213], v[54:57]
	v_mfma_f32_16x16x32_bf16 v[182:185], v[198:201], v[78:81], v[134:137]
	v_mfma_f32_16x16x32_bf16 v[134:137], v[198:201], v[224:227], v[34:37]
	v_mfma_f32_16x16x32_bf16 v[34:37], v[202:205], v[210:213], v[58:61]
	v_mfma_f32_16x16x32_bf16 v[130:133], v[206:209], v[224:227], v[34:37]
	s_setprio 0
	s_barrier
; #define PG8_STAGE(bufoff, gbase, voff) do { _Pragma("unroll") for (int _i = 0; _i < 2; ++_i) \
;         __builtin_amdgcn_global_load_lds((const unsigned*)((const char*)(gbase) + (size_t)_i * r64 + (voff)), (PG8_LAS unsigned*)(lds + (bufoff) + ldsw + _i * 8192), 16, 0, 0); } while (0)
; #define PG8_LDA(dst, b, h) do { _Pragma("unroll") for (int m = 0; m < 4; ++m) _Pragma("unroll") for (int k = 0; k < 2; ++k) dst[m][k] = *(const PG8_LAS bf16x8*)(lds + PG8_SA(b, h) + aoff + m * 2048 + k * 1024); } while (0)
; #define PG8_MMA(ai, bj, At, Bt) do { __builtin_amdgcn_s_setprio(1); _Pragma("unroll") for (int m = 0; m < 4; ++m) _Pragma("unroll") for (int n = 0; n < 2; ++n) _Pragma("unroll") for (int k = 0; k < 2; ++k) \
;         acc[ai][bj][m][n] = __builtin_amdgcn_mfma_f32_16x16x32_bf16(Bt[n][k], At[m][k], acc[ai][bj][m][n], 0, 0, 0); __builtin_amdgcn_s_setprio(0); } while (0)
; #define PG8_WAIT_V(n) asm volatile("s_waitcnt vmcnt(" #n ")" ::: "memory")
; #define PG8_WAIT_L(n) asm volatile("s_waitcnt lgkmcnt(" #n ")" ::: "memory")
; #define PG8_BAR __builtin_amdgcn_s_barrier()
; #define PG8_SCHED __builtin_amdgcn_sched_barrier(0)
; template <class Epi, class Sched, bool ALIGN_EPI = false, bool SP2 = false>
; __device__ __forceinline__ void gemm_phase(PG8_LAS unsigned char* lds, const Gemm g, const Sched& S, const Epi& E) {
;     ...
;             PG8_WAIT_V(8); PG8_WAIT_L(0); PG8_BAR; PG8_MMA(0, 0, At, B0); PG8_MMA(0, 1, At, B1); PG8_BAR; PG8_SCHED;
;             PG8_LDA(At, 1, 1); PG8_STAGE(PG8_SB(1, 0), b3, voffB); PG8_STAGE(PG8_SB(1, 1), b3 + hstep, voffB); PG8_STAGE(PG8_SA(1, 0), a3, voffA);
;             PG8_WAIT_V(8); PG8_WAIT_L(0); PG8_BAR; PG8_MMA(1, 0, At, B0); PG8_MMA(1, 1, At, B1); PG8_BAR; PG8_SCHED;
	s_add_i32 s3, s3, s41
	v_lshl_add_u64 v[74:75], v[228:229], 0, s[34:35]
	s_mov_b32 m0, s3
	s_nop 1
	ds_read_b128 v[34:37], v243 offset:49152
	ds_read_b128 v[38:41], v243 offset:50176
	ds_read_b128 v[42:45], v243 offset:51200
	ds_read_b128 v[46:49], v243 offset:52224
	ds_read_b128 v[50:53], v243 offset:53248
	ds_read_b128 v[54:57], v243 offset:54272
	ds_read_b128 v[58:61], v243 offset:55296
	ds_read_b128 v[210:213], v243 offset:56320
	global_load_lds_dwordx4 v[74:75], off
	v_lshl_add_u64 v[74:75], v[230:231], 0, s[34:35]
	s_add_i32 m0, s3, 0x2000
	s_add_i32 s3, s13, s41
	global_load_lds_dwordx4 v[74:75], off
	v_lshl_add_u64 v[74:75], v[244:245], 0, s[34:35]
	s_mov_b32 m0, s3
	s_nop 0
	global_load_lds_dwordx4 v[74:75], off
	v_lshl_add_u64 v[74:75], v[246:247], 0, s[34:35]
	s_add_i32 m0, s3, 0x2000
	s_nop 0
	global_load_lds_dwordx4 v[74:75], off
	v_lshl_add_u64 v[74:75], v[248:249], 0, s[34:35]
	s_mov_b32 m0, s81
	s_nop 0
	global_load_lds_dwordx4 v[74:75], off
	v_lshl_add_u64 v[74:75], v[250:251], 0, s[34:35]
	s_mov_b32 m0, s1
	s_nop 0
	global_load_lds_dwordx4 v[74:75], off
	s_waitcnt vmcnt(8)
	s_waitcnt lgkmcnt(0)
	s_barrier
	s_setprio 1
	s_waitcnt lgkmcnt(0)
	v_mfma_f32_16x16x32_bf16 v[74:77], v[26:29], v[34:37], v[126:129]
	v_mfma_f32_16x16x32_bf16 v[126:129], v[30:33], v[38:41], v[74:77]
	v_mfma_f32_16x16x32_bf16 v[74:77], v[66:69], v[34:37], v[122:125]
	v_mfma_f32_16x16x32_bf16 v[122:125], v[70:73], v[38:41], v[74:77]
	v_mfma_f32_16x16x32_bf16 v[74:77], v[26:29], v[42:45], v[110:113]
	v_mfma_f32_16x16x32_bf16 v[110:113], v[30:33], v[46:49], v[74:77]
	v_mfma_f32_16x16x32_bf16 v[74:77], v[66:69], v[42:45], v[106:109]
	v_mfma_f32_16x16x32_bf16 v[106:109], v[70:73], v[46:49], v[74:77]
	v_mfma_f32_16x16x32_bf16 v[74:77], v[26:29], v[50:53], v[94:97]
	v_mfma_f32_16x16x32_bf16 v[2:5], v[26:29], v[58:61], v[2:5]
	v_mfma_f32_16x16x32_bf16 v[94:97], v[30:33], v[54:57], v[74:77]
	v_mfma_f32_16x16x32_bf16 v[74:77], v[66:69], v[50:53], v[90:93]
	v_mfma_f32_16x16x32_bf16 v[78:81], v[30:33], v[210:213], v[2:5]
	v_mfma_f32_16x16x32_bf16 v[2:5], v[66:69], v[58:61], v[6:9]
	v_mfma_f32_16x16x32_bf16 v[90:93], v[70:73], v[54:57], v[74:77]
	v_mfma_f32_16x16x32_bf16 v[74:77], v[70:73], v[210:213], v[2:5]
	s_setprio 0
	s_setprio 1
	v_mfma_f32_16x16x32_bf16 v[2:5], v[194:197], v[34:37], v[10:13]
	v_mfma_f32_16x16x32_bf16 v[118:121], v[198:201], v[38:41], v[2:5]
	v_mfma_f32_16x16x32_bf16 v[2:5], v[202:205], v[34:37], v[14:17]
	v_mfma_f32_16x16x32_bf16 v[114:117], v[206:209], v[38:41], v[2:5]
	v_mfma_f32_16x16x32_bf16 v[2:5], v[194:197], v[42:45], v[62:65]
	v_mfma_f32_16x16x32_bf16 v[102:105], v[198:201], v[46:49], v[2:5]
	v_mfma_f32_16x16x32_bf16 v[2:5], v[202:205], v[42:45], v[98:101]
	v_mfma_f32_16x16x32_bf16 v[98:101], v[206:209], v[46:49], v[2:5]
	v_mfma_f32_16x16x32_bf16 v[2:5], v[194:197], v[50:53], v[86:89]
	v_mfma_f32_16x16x32_bf16 v[86:89], v[198:201], v[54:57], v[2:5]
	v_mfma_f32_16x16x32_bf16 v[2:5], v[202:205], v[50:53], v[82:85]
	v_mfma_f32_16x16x32_bf16 v[82:85], v[206:209], v[54:57], v[2:5]
	v_mfma_f32_16x16x32_bf16 v[2:5], v[194:197], v[58:61], v[18:21]
	v_mfma_f32_16x16x32_bf16 v[70:73], v[198:201], v[210:213], v[2:5]
	v_mfma_f32_16x16x32_bf16 v[2:5], v[202:205], v[58:61], v[22:25]
	v_mfma_f32_16x16x32_bf16 v[66:69], v[206:209], v[210:213], v[2:5]
	s_setprio 0
	s_barrier
	s_add_u32 s6, s6, 0x100
	s_addc_u32 s7, s7, 0
	s_add_u32 s10, s10, 0x100
	s_addc_u32 s11, s11, 0
	s_cmp_ge_u32 s12, s2
	s_mov_b32 s8, s12
	s_cbranch_scc1 .Lkloop_done
